# dn_out: per-item norm-gain loads hoisted out of the item loop into persistent registers, so the next item's prefetch loads are no longer forced complete mid-epilogue
# baseline (speedup 1.0000x reference)
; #define LAS __attribute__((address_space(3)))
; __device__ __forceinline__ void dn_out_phase(const Args& a, LAS unsigned char* lds, int c, int G, int tid, int wave, int lane) {
;     unsigned char* ws = a.ws; bf16* Y = (bf16*)(ws + WS_Y);
;     int item = dn_item_of(c, 0, G); if (item < 0) return;
;     OutPre p; out_load(p, a, item, tid, wave, lane);
;     const int ti = wave & 1, te = wave >> 1, rr = lane & 31, hh = lane >> 5, e = 32 * te + rr;
;     LAS float* of = (LAS float*)lds;
; #pragma unroll 1
;     for (int k = 0; item >= 0; ++k) {
;         const int h = item & 3, n = (item >> 2) & (NCH - 1), b = item >> 9; const int tok0 = b * T + n * 64;
;     ...
;           const float* dw = a.in[14] + e0; float o[16];
.LBB0_1134:
	s_lshl_b32 s21, s2, 5
	s_ashr_i32 s13, s3, 3
	s_ashr_i32 s14, s2, 3
	s_and_b32 s22, s21, 0x80
	s_and_b32 s23, s2, 3
	s_lshl_b32 s20, s20, 1
	s_add_u32 s20, s92, s20
	s_addc_u32 s21, s93, 0
	s_lshl_b64 s[16:17], s[16:17], 1
	v_lshlrev_b32_e32 v108, 1, v0
	v_mov_b32_e32 v109, 0
	s_add_u32 s16, s92, s16
	v_lshlrev_b32_e32 v2, 2, v1
	v_lshl_add_u64 v[0:1], s[20:21], 0, v[108:109]
	s_mov_b64 s[20:21], 0xec00000
	s_addc_u32 s17, s93, s17
	v_lshl_add_u64 v[110:111], v[0:1], 0, s[20:21]
	v_lshl_add_u64 v[0:1], s[16:17], 0, v[108:109]
	s_mov_b64 s[16:17], 0xcc00000
	v_lshl_add_u64 v[112:113], v[0:1], 0, s[16:17]
	s_lshl_b32 s16, s64, 5
	v_and_b32_e32 v0, 4, v116
	v_and_or_b32 v0, s16, 32, v0
	s_abs_i32 s16, s13
	v_cvt_f32_u32_e32 v1, s16
	s_lshl_b32 s17, s64, 6
	s_and_b32 s17, s17, 0xffffff80
	v_and_b32_e32 v3, 31, v206
	v_rcp_iflag_f32_e32 v1, v1
	s_add_i32 s17, s17, 0
	v_lshl_add_u32 v5, v3, 2, s17
	v_mov_b32_e32 v3, v109
	v_mul_f32_e32 v1, 0x4f7ffffe, v1
	v_cvt_u32_f32_e32 v1, v1
	s_waitcnt lgkmcnt(0)
	v_lshl_add_u64 v[114:115], s[18:19], 0, v[2:3]
	global_load_dwordx4 v[148:151], v[114:115], off
	global_load_dwordx4 v[152:155], v[114:115], off offset:16
	global_load_dwordx4 v[156:159], v[114:115], off offset:48
	global_load_dwordx4 v[160:163], v[114:115], off offset:32
	s_sub_i32 s17, 0, s16
	v_mul_u32_u24_e32 v0, 0x210, v0
	v_readfirstlane_b32 s18, v1
	s_mul_i32 s17, s17, s18
	s_mul_hi_u32 s17, s18, s17
	s_add_i32 s18, s18, s17
	s_lshr_b32 s17, s18, 25
	s_mul_i32 s17, s17, s16
	s_sub_i32 s17, 0x80, s17
	s_sub_i32 s18, s17, s16
	s_cmp_ge_u32 s17, s16
	s_cselect_b32 s17, s18, s17
	s_sub_i32 s18, s17, s16
	s_cmp_ge_u32 s17, s16
	s_cselect_b32 s16, s18, s17
	s_cmp_lg_u32 s16, 0
	s_cselect_b64 s[16:17], -1, 0
	s_add_i32 s28, s14, s13
	s_add_i32 s14, s28, s22
	v_add_u32_e32 v4, 0, v2
	v_mul_u32_u24_e32 v6, 0x210, v116
	s_lshl_b32 s14, s14, 2
	s_mov_b32 s20, 0xfffe0000
	v_add_u32_e32 v119, v5, v0
	v_mbcnt_lo_u32_b32 v0, -1, 0
	s_mov_b32 s15, 0
	s_or_b32 s29, s14, s23
	s_ashr_i32 s30, s3, 1
	s_add_i32 s31, s2, s3
	s_movk_i32 s33, 0x1800
	s_mov_b64 s[18:19], 0x4c01400
	s_mov_b32 s34, 0x4c01000
	s_mov_b32 s21, -1
	s_waitcnt vmcnt(8)
	v_add_u32_e32 v120, v4, v6
	v_mbcnt_hi_u32_b32 v121, -1, v0
	v_mov_b32_e32 v122, 0x358637bd
	s_mov_b32 s35, 0x800000
	s_mov_b64 s[22:23], 0xac00400
	s_mov_b32 s36, 0xac00000
	s_branch .LBB0_1137

; #define LAS __attribute__((address_space(3)))
; __device__ __forceinline__ float lo_bf(unsigned w) { return __uint_as_float(w << 16); }
; __device__ __forceinline__ float hi_bf(unsigned w) { return __uint_as_float(w & 0xffff0000u); }
; __device__ __forceinline__ unsigned pk2(float lo, float hi) { const f32x2_t v = {lo, hi}; const bf16x2_t b = __builtin_convertvector(v, bf16x2_t); return __builtin_bit_cast(unsigned, b); }
; #define WG_BAR() do { asm volatile("s_waitcnt lgkmcnt(0)" ::: "memory"); __builtin_amdgcn_s_barrier(); asm volatile("" ::: "memory"); } while (0)
; __device__ __forceinline__ void dn_out_phase(const Args& a, LAS unsigned char* lds, int c, int G, int tid, int wave, int lane) {
;     ...
;         for (int r = 0; r < 16; ++r) { const int i = 32 * ti + (r & 3) + 8 * (r >> 2) + 4 * hh; of[i * 132 + e] = acc[r]; }
;         WG_BAR();
;         { const int i = tid >> 3, e0 = 16 * (tid & 7);
;           float v[16]; float sq = 0.f;
; #pragma unroll
;           for (int q = 0; q < 4; ++q) { const f32x4 t = *(const LAS f32x4*)(of + i * 132 + e0 + 4 * q); v[4 * q] = t[0]; v[4 * q + 1] = t[1]; v[4 * q + 2] = t[2]; v[4 * q + 3] = t[3]; sq += (t[0] * t[0] + t[1] * t[1]) + (t[2] * t[2] + t[3] * t[3]); }
;           sq += __shfl_xor(sq, 1); sq += __shfl_xor(sq, 2); sq += __shfl_xor(sq, 4);
;           const float rs = rsqrtf(sq * (1.0f / 128.0f) + EPS);
;           const float zz[16] = { lo_bf(z0.x), hi_bf(z0.x), lo_bf(z0.y), hi_bf(z0.y), lo_bf(z0.z), hi_bf(z0.z), lo_bf(z0.w), hi_bf(z0.w), lo_bf(z1.x), hi_bf(z1.x), lo_bf(z1.y), hi_bf(z1.y), lo_bf(z1.z), hi_bf(z1.z), lo_bf(z1.w), hi_bf(z1.w) };
;           const float* dw = a.in[14] + e0; float o[16];
; #pragma unroll
;           for (int q = 0; q < 16; ++q) o[q] = v[q] * rs * dw[q] * zz[q];
;           v4u w0, w1; w0.x = pk2(o[0], o[1]); w0.y = pk2(o[2], o[3]); w0.z = pk2(o[4], o[5]); w0.w = pk2(o[6], o[7]); w1.x = pk2(o[8], o[9]); w1.y = pk2(o[10], o[11]); w1.z = pk2(o[12], o[13]); w1.w = pk2(o[14], o[15]);
;           v4u* yp = (v4u*)(Y + (size_t)(tok0 + i) * D + 512 + 128 * h + e0); yp[0] = w0; yp[1] = w1; }
;         WG_BAR();
.LBB0_1136:
	s_nop 3
	ds_write2_b32 v119, v0, v1 offset1:132
	v_add_u32_e32 v0, 0x400, v119
	ds_write2_b32 v0, v2, v3 offset0:8 offset1:140
	v_add_u32_e32 v0, 0x1000, v119
	ds_write2_b32 v0, v4, v5 offset0:32 offset1:164
	v_add_u32_e32 v0, 0x1400, v119
	ds_write2_b32 v0, v6, v7 offset0:40 offset1:172
	v_add_u32_e32 v0, 0x2000, v119
	ds_write2_b32 v0, v8, v9 offset0:64 offset1:196
	v_add_u32_e32 v0, 0x2400, v119
	ds_write2_b32 v0, v10, v11 offset0:72 offset1:204
	v_add_u32_e32 v0, 0x3000, v119
	ds_write2_b32 v0, v12, v13 offset0:96 offset1:228
	v_add_u32_e32 v0, 0x3400, v119
	ds_write2_b32 v0, v14, v15 offset0:104 offset1:236
	s_waitcnt lgkmcnt(0)
	s_barrier
	ds_read_b128 v[0:3], v120
	ds_read_b128 v[12:15], v120 offset:16
	ds_read_b128 v[124:127], v120 offset:32
	ds_read_b128 v[128:131], v120 offset:48
	s_lshl_b32 s14, s12, 4
	s_and_b32 s14, s14, 0x7fffe000
	s_waitcnt lgkmcnt(3)
	v_pk_mul_f32 v[132:133], v[2:3], v[2:3]
	v_pk_mul_f32 v[134:135], v[0:1], v[0:1]
	s_waitcnt lgkmcnt(0)
	v_mul_f32_e32 v105, v128, v128
	v_pk_mov_b32 v[136:137], v[134:135], v[132:133] op_sel:[1,0]
	v_mov_b32_e32 v135, v133
	v_pk_add_f32 v[140:141], v[136:137], v[134:135]
	v_pk_mul_f32 v[132:133], v[14:15], v[14:15]
	v_pk_mul_f32 v[134:135], v[12:13], v[12:13]
	v_mul_f32_e32 v107, v129, v129
	v_pk_mov_b32 v[136:137], v[134:135], v[132:133] op_sel:[1,0]
	v_mov_b32_e32 v135, v133
	v_pk_add_f32 v[142:143], v[136:137], v[134:135]
	v_pk_add_f32 v[140:141], v[140:141], v[140:141] op_sel:[0,1] op_sel_hi:[1,0]
	v_pk_add_f32 v[142:143], v[142:143], v[142:143] op_sel:[0,1] op_sel_hi:[1,0]
	v_mov_b32_e32 v141, v105
	v_mov_b32_e32 v143, v107
	v_mul_f32_e32 v108, v125, v125
	v_pk_add_f32 v[140:141], v[140:141], v[142:143]
	v_pk_fma_f32 v[142:143], v[124:125], v[124:125], v[108:109] op_sel_hi:[1,1,0]
	v_mul_f32_e32 v108, v127, v127
	v_mul_f32_e32 v123, v130, v130
	v_mul_f32_e32 v146, v131, v131
	v_pk_fma_f32 v[144:145], v[126:127], v[126:127], v[108:109] op_sel_hi:[1,1,0]
	v_and_b32_e32 v108, 64, v121
	v_mov_b32_e32 v143, v123
	v_mov_b32_e32 v145, v146
	v_xor_b32_e32 v107, 1, v121
	v_add_u32_e32 v108, 64, v108
	v_pk_add_f32 v[142:143], v[142:143], v[144:145]
	v_cmp_lt_i32_e32 vcc, v107, v108
	v_pk_add_f32 v[140:141], v[140:141], v[142:143]
	s_lshl_b32 s12, s12, 8
	v_cndmask_b32_e32 v107, v121, v107, vcc
	v_add_f32_e32 v105, v140, v141
	v_lshlrev_b32_e32 v107, 2, v107
	ds_bpermute_b32 v107, v107, v105
	v_lshlrev_b32_e32 v140, 16, v28
	v_and_b32_e32 v141, 0xffff0000, v28
	s_add_i32 s29, s29, s30
	s_add_i32 s28, s28, s13
	s_waitcnt lgkmcnt(0)
	v_add_f32_e32 v105, v105, v107
	v_xor_b32_e32 v107, 2, v121
	v_cmp_lt_i32_e32 vcc, v107, v108
	s_add_i32 s31, s31, s3
	s_nop 0
	v_cndmask_b32_e32 v107, v121, v107, vcc
	v_lshlrev_b32_e32 v107, 2, v107
	ds_bpermute_b32 v107, v107, v105
	s_waitcnt lgkmcnt(0)
	v_add_f32_e32 v105, v105, v107
	v_xor_b32_e32 v107, 4, v121
	v_cmp_lt_i32_e32 vcc, v107, v108
	s_nop 1
	v_cndmask_b32_e32 v107, v121, v107, vcc
	v_lshlrev_b32_e32 v107, 2, v107
	ds_bpermute_b32 v107, v107, v105
	s_waitcnt lgkmcnt(0)
	v_add_f32_e32 v105, v105, v107
	v_fmamk_f32 v105, v105, 0x3c000000, v122
	v_mul_f32_e32 v107, 0x4b800000, v105
	v_cmp_gt_f32_e32 vcc, s35, v105
	s_nop 1
	v_cndmask_b32_e32 v105, v105, v107, vcc
	v_rsq_f32_e32 v105, v105
	s_nop 0
	v_mul_f32_e32 v107, 0x45800000, v105
	v_cndmask_b32_e32 v108, v105, v107, vcc
	v_pk_mul_f32 v[0:1], v[0:1], v[108:109] op_sel_hi:[1,0]
	v_pk_mul_f32 v[2:3], v[2:3], v[108:109] op_sel_hi:[1,0]
	s_nop 0
	v_pk_mul_f32 v[0:1], v[148:149], v[0:1]
	v_lshlrev_b32_e32 v4, 16, v29
	v_and_b32_e32 v5, 0xffff0000, v29
	v_pk_mul_f32 v[2:3], v[150:151], v[2:3]
	v_pk_mul_f32 v[6:7], v[12:13], v[108:109] op_sel_hi:[1,0]
	v_pk_mul_f32 v[2:3], v[2:3], v[4:5]
	v_lshlrev_b32_e32 v4, 16, v30
	v_and_b32_e32 v5, 0xffff0000, v30
	s_nop 0
	v_pk_mul_f32 v[6:7], v[152:153], v[6:7]
	v_pk_mul_f32 v[8:9], v[14:15], v[108:109] op_sel_hi:[1,0]
	v_pk_mul_f32 v[4:5], v[6:7], v[4:5]
	v_lshlrev_b32_e32 v6, 16, v31
	v_and_b32_e32 v7, 0xffff0000, v31
	v_pk_mul_f32 v[8:9], v[154:155], v[8:9]
	v_pk_mul_f32 v[10:11], v[124:125], v[108:109] op_sel_hi:[1,0]
	v_pk_mul_f32 v[6:7], v[8:9], v[6:7]
	v_lshlrev_b32_e32 v8, 16, v24
	v_and_b32_e32 v9, 0xffff0000, v24
	s_nop 0
	v_pk_mul_f32 v[10:11], v[160:161], v[10:11]
	v_pk_mul_f32 v[0:1], v[0:1], v[140:141]
	v_pk_mul_f32 v[8:9], v[10:11], v[8:9]
	v_cvt_pk_bf16_f32 v0, v0, v1
	v_cvt_pk_bf16_f32 v1, v2, v3
	v_cvt_pk_bf16_f32 v2, v4, v5
	v_cvt_pk_bf16_f32 v4, v8, v9
	v_or_b32_e32 v8, s14, v116
	v_lshlrev_b32_e32 v10, 16, v25
	v_and_b32_e32 v11, 0xffff0000, v25
	v_pk_mul_f32 v[12:13], v[126:127], v[108:109] op_sel_hi:[1,0]
	v_pk_mul_f32 v[14:15], v[128:129], v[108:109] op_sel_hi:[1,0]
	v_pk_mul_f32 v[24:25], v[130:131], v[108:109] op_sel_hi:[1,0]
	v_lshl_add_u32 v108, s37, 6, v8
	v_lshlrev_b64 v[8:9], 11, v[108:109]
	v_lshl_add_u64 v[8:9], s[92:93], 0, v[8:9]
	s_and_b32 s14, s12, 0x300
	v_pk_mul_f32 v[12:13], v[162:163], v[12:13]
	v_lshl_add_u64 v[8:9], v[8:9], 0, s[14:15]
	v_mov_b32_e32 v105, v109
	v_pk_mul_f32 v[10:11], v[12:13], v[10:11]
	v_lshlrev_b32_e32 v12, 16, v26
	v_and_b32_e32 v13, 0xffff0000, v26
	v_pk_mul_f32 v[14:15], v[14:15], v[156:157]
	v_lshl_add_u64 v[8:9], v[8:9], 0, v[104:105]
	v_pk_mul_f32 v[12:13], v[14:15], v[12:13]
	v_lshlrev_b32_e32 v14, 16, v27
	v_and_b32_e32 v15, 0xffff0000, v27
	v_pk_mul_f32 v[24:25], v[24:25], v[158:159]
	v_cvt_pk_bf16_f32 v5, v10, v11
	v_lshl_add_u64 v[10:11], v[8:9], 0, s[22:23]
	v_add_co_u32_e32 v8, vcc, s36, v8
	v_pk_mul_f32 v[14:15], v[24:25], v[14:15]
	v_cvt_pk_bf16_f32 v3, v6, v7
	v_addc_co_u32_e32 v9, vcc, 0, v9, vcc
	v_cvt_pk_bf16_f32 v6, v12, v13
	v_cvt_pk_bf16_f32 v7, v14, v15
	global_store_dwordx4 v[8:9], v[0:3], off offset:1024
	global_store_dwordx4 v[10:11], v[4:7], off offset:16
	s_waitcnt lgkmcnt(0)
	s_barrier
	v_mov_b64_e32 v[28:29], v[100:101]
	v_mov_b64_e32 v[24:25], v[96:97]
	s_andn2_b64 vcc, exec, s[26:27]
	s_mov_b32 s12, s24
	v_mov_b64_e32 v[30:31], v[102:103]
	v_mov_b64_e32 v[26:27], v[98:99]
	s_cbranch_vccz .LBB0_1148
